# stream attention units: wave ids 4/5 and 6/7 relabelled so the two computing waves run on different SIMDs
# baseline (speedup 1.0000x reference)
.LBB0_879:
	s_add_i32 s10, s72, 1
	v_cvt_f32_u32_e32 v2, s10
	s_mov_b64 s[40:41], -1
	v_mul_f32_e32 v3, -0.5, v2
	v_cmp_gt_f32_e32 vcc, s14, v3
	s_and_b64 s[10:11], vcc, exec
	s_cselect_b32 s10, 0xffffffc0, 0
	v_cndmask_b32_e32 v3, 0, v224, vcc
	v_fmac_f32_e32 v3, -0.5, v2
	v_exp_f32_e32 v2, v3
	s_and_b64 vcc, exec, s[38:39]
	v_ldexp_f32 v2, v2, s10
	v_mul_f32_e32 v164, 0x3fb8aa3b, v2
	s_cbranch_vccz .LBB0_958
	v_readlane_b32 s10, v255, 19
	v_lshrrev_b32_e32 v153, 2, v0
	v_and_b32_e32 v153, 64, v153
	v_xor_b32_e32 v153, v0, v153
	s_lshl_b32 s74, s72, 8
	v_mov_b32_e32 v2, s10
	ds_read_b32 v152, v2
	v_mov_b32_e32 v121, v67
	v_and_b32_e32 v151, 31, v153
	v_add_u32_e32 v2, s34, v151
	v_readfirstlane_b32 s10, v153
	v_ashrrev_i32_e32 v3, 31, v2
	s_ashr_i32 s11, s10, 8
	v_lshlrev_b64 v[2:3], 12, v[2:3]
	v_lshl_add_u64 v[2:3], s[36:37], 0, v[2:3]
	s_lshl_b32 s12, s11, 6
	v_bfe_u32 v150, v153, 5, 1
	v_lshl_add_u64 v[2:3], v[2:3], 0, s[74:75]
	s_ashr_i32 s13, s12, 31
	v_lshl_add_u64 v[2:3], s[12:13], 1, v[2:3]
	v_lshlrev_b32_e32 v120, 4, v150
	v_lshl_add_u64 v[2:3], v[2:3], 0, v[120:121]
	global_load_dwordx4 v[68:71], v[2:3], off
	global_load_dwordx4 v[72:75], v[2:3], off offset:32
	global_load_dwordx4 v[76:79], v[2:3], off offset:64
	global_load_dwordx4 v[116:119], v[2:3], off offset:96
	s_ashr_i32 s12, s10, 6
	v_bfe_u32 v121, v153, 4, 2
	v_lshl_or_b32 v2, s12, 3, v121
	v_ashrrev_i32_e32 v3, 31, v2
	v_and_b32_e32 v127, 15, v153
	v_lshlrev_b64 v[4:5], 12, v[2:3]
	v_bitop3_b32 v8, v2, v127, 11 bitop3:0x6c
	v_or_b32_e32 v6, 4, v2
	v_bitop3_b32 v9, v2, v153, 4 bitop3:0x36
	s_lshl_b32 s13, s12, 5
	v_bfe_u32 v2, v153, 2, 4
	v_ashrrev_i32_e32 v7, 31, v6
	v_and_or_b32 v2, s13, 32, v2
	v_lshlrev_b64 v[6:7], 12, v[6:7]
	v_lshlrev_b32_e32 v66, 12, v2
	v_lshl_add_u64 v[4:5], s[44:45], 0, v[4:5]
	v_lshl_add_u64 v[6:7], s[44:45], 0, v[6:7]
	v_lshl_add_u64 v[2:3], s[46:47], 0, v[66:67]
	s_ashr_i32 s13, s10, 2
	v_lshl_add_u64 v[4:5], v[4:5], 0, s[74:75]
	v_lshlrev_b32_e32 v66, 4, v8
	s_and_b32 s14, s13, 0xffffffe0
	v_lshlrev_b32_e32 v10, 3, v153
	v_lshl_add_u64 v[80:81], v[4:5], 0, v[66:67]
	v_lshl_add_u64 v[4:5], v[6:7], 0, s[74:75]
	v_lshlrev_b32_e32 v6, 4, v9
	s_ashr_i32 s15, s14, 31
	v_and_b32_e32 v154, 24, v10
	v_and_b32_e32 v66, 0xf0, v6
	v_lshl_add_u64 v[2:3], v[2:3], 0, s[74:75]
	s_max_i32 s74, s73, 0
	s_lshl_b32 s12, s12, 11
	v_lshl_add_u64 v[122:123], v[4:5], 0, v[66:67]
	v_lshl_add_u64 v[2:3], s[14:15], 1, v[2:3]
	v_lshlrev_b32_e32 v66, 1, v154
	s_waitcnt vmcnt(0)
	s_lshl_b64 s[14:15], s[74:75], 12
	s_add_i32 s12, s12, 0
	v_lshl_add_u64 v[124:125], v[2:3], 0, v[66:67]
	v_lshl_add_u64 v[2:3], v[80:81], 0, s[14:15]
	s_mov_b32 s16, m0
	s_mov_b32 m0, s12
	s_nop 0
	global_load_lds_dwordx4 v[2:3], off
	s_mov_b32 m0, s16
	v_lshl_add_u64 v[2:3], v[122:123], 0, s[14:15]
	s_add_i32 s16, s12, 0x400
	s_mov_b32 s17, m0
	s_mov_b32 m0, s16
	s_nop 0
	global_load_lds_dwordx4 v[2:3], off
	s_mov_b32 m0, s17
	s_add_i32 s13, s12, 0x10000
	v_lshl_add_u64 v[2:3], v[124:125], 0, s[14:15]
	s_mov_b32 s14, m0
	s_mov_b32 m0, s13
	s_nop 0
	global_load_lds_dwordx4 v[2:3], off
	s_mov_b32 m0, s14
	s_mov_b64 s[14:15], 0x10000
	v_lshl_add_u64 v[2:3], v[2:3], 0, s[14:15]
	s_add_i32 s14, s13, 0x400
	s_mov_b32 s15, m0
	s_mov_b32 m0, s14
	s_nop 0
	global_load_lds_dwordx4 v[2:3], off
	s_mov_b32 m0, s15
	s_cmp_lt_i32 s77, 2
	s_cselect_b64 s[40:41], -1, 0
	s_and_b64 vcc, exec, s[40:41]
	s_cbranch_vccnz .LBB0_882
	s_max_i32 s14, s73, 64
	s_sub_i32 s14, s14, 64
	s_mov_b32 s15, s75
	s_lshl_b64 s[14:15], s[14:15], 12
	v_lshl_add_u64 v[2:3], v[80:81], 0, s[14:15]
	s_add_i32 s16, s12, 0x4000
	s_mov_b32 s17, m0
	s_mov_b32 m0, s16
	s_nop 0
	global_load_lds_dwordx4 v[2:3], off
	s_mov_b32 m0, s17
	v_lshl_add_u64 v[2:3], v[122:123], 0, s[14:15]
	s_add_i32 s16, s12, 0x4400
	s_mov_b32 s17, m0
	s_mov_b32 m0, s16
	s_nop 0
	global_load_lds_dwordx4 v[2:3], off
	s_mov_b32 m0, s17
	v_lshl_add_u64 v[2:3], v[124:125], 0, s[14:15]
	s_add_i32 s14, s13, 0x4000
	s_mov_b32 s15, m0
	s_mov_b32 m0, s14
	s_nop 0
	global_load_lds_dwordx4 v[2:3], off
	s_mov_b32 m0, s15
	s_mov_b64 s[14:15], 0x10000
	v_lshl_add_u64 v[2:3], v[2:3], 0, s[14:15]
	s_add_i32 s14, s13, 0x4400
	s_mov_b32 s15, m0
	s_mov_b32 m0, s14
	s_nop 0
	global_load_lds_dwordx4 v[2:3], off
	s_mov_b32 m0, s15
